# final RMSNorm phase: hand-written fast path (gain vector in registers instead of reloaded per chunk behind store-draining waits, rows prefetched four deep, DPP wave reduction, XCD-aware row blocks)
# speedup vs baseline: 1.0085x; 1.0085x over previous
.LBB0_1287:
	s_cmp_lt_i32 s50, 43
	s_cselect_b64 s[0:1], -1, 0
	s_cmp_gt_i32 s51, 42
	s_cselect_b64 s[2:3], -1, 0
	s_and_b64 s[0:1], s[0:1], s[2:3]
	s_and_b64 vcc, exec, s[0:1]
	s_cbranch_vccz .LBB0_1291
	v_readlane_b32 s1, v254, 16
	v_readfirstlane_b32 s0, v0
	s_ashr_i32 s0, s0, 6
	s_add_i32 s8, s0, s1
	s_cmpk_gt_i32 s8, 0x3fff
	s_cbranch_scc1 .LBB0_1291
	v_readlane_b32 s2, v253, 2
	v_readlane_b32 s3, v253, 3
	s_nop 4
	s_load_dword s1, s[2:3], 0x0
	s_load_dwordx4 s[4:7], s[96:97], 0xa8
	s_load_dwordx2 s[10:11], s[96:97], 0xb8
	v_and_b32_e32 v35, 63, v0
	v_lshlrev_b32_e32 v36, 4, v35
	v_lshlrev_b32_e32 v37, 5, v35
	s_waitcnt lgkmcnt(0)
	s_cmp_lg_u32 s1, 0x100
	s_cbranch_scc1 .Lfn_orig
	s_lshr_b32 s12, s8, 3
	s_and_b32 s13, s12, 7
	s_lshl_b32 s13, s13, 5
	s_lshr_b32 s12, s12, 3
	s_or_b32 s12, s12, s13
	s_lshl_b32 s12, s12, 3
	s_and_b32 s13, s8, 7
	s_or_b32 s12, s12, s13
	s_lshl_b32 s13, s12, 15
	s_add_u32 s10, s10, s13
	s_addc_u32 s11, s11, 0
	s_add_u32 s10, s10, 0x19624000
	s_addc_u32 s11, s11, 0
	s_lshl_b32 s13, s12, 16
	s_add_u32 s20, s6, s13
	s_addc_u32 s21, s7, 0
	s_mov_b64 s[12:13], s[4:5]
	global_load_dwordx4 v[100:103], v36, s[10:11]
	global_load_dwordx4 v[104:107], v36, s[10:11] offset:1024
	global_load_dwordx4 v[108:111], v36, s[10:11] offset:2048
	global_load_dwordx4 v[112:115], v36, s[10:11] offset:3072
	s_add_u32 s10, s10, 0x1000
	s_addc_u32 s11, s11, 0
	global_load_dwordx4 v[2:5], v37, s[12:13]
	global_load_dwordx4 v[6:9], v37, s[12:13] offset:16
	global_load_dwordx4 v[10:13], v37, s[12:13] offset:2048
	global_load_dwordx4 v[14:17], v37, s[12:13] offset:2064
	s_add_u32 s12, s12, 0x1000
	s_addc_u32 s13, s13, 0
	global_load_dwordx4 v[18:21], v37, s[12:13]
	global_load_dwordx4 v[22:25], v37, s[12:13] offset:16
	global_load_dwordx4 v[26:29], v37, s[12:13] offset:2048
	global_load_dwordx4 v[30:33], v37, s[12:13] offset:2064
	global_load_dwordx4 v[116:119], v36, s[10:11]
	global_load_dwordx4 v[120:123], v36, s[10:11] offset:1024
	global_load_dwordx4 v[124:127], v36, s[10:11] offset:2048
	global_load_dwordx4 v[128:131], v36, s[10:11] offset:3072
	s_add_u32 s10, s10, 0x1000
	s_addc_u32 s11, s11, 0
	global_load_dwordx4 v[132:135], v36, s[10:11]
	global_load_dwordx4 v[136:139], v36, s[10:11] offset:1024
	global_load_dwordx4 v[140:143], v36, s[10:11] offset:2048
	global_load_dwordx4 v[144:147], v36, s[10:11] offset:3072
	s_add_u32 s10, s10, 0x1000
	s_addc_u32 s11, s11, 0
	global_load_dwordx4 v[148:151], v36, s[10:11]
	global_load_dwordx4 v[152:155], v36, s[10:11] offset:1024
	global_load_dwordx4 v[156:159], v36, s[10:11] offset:2048
	global_load_dwordx4 v[160:163], v36, s[10:11] offset:3072
	s_add_u32 s10, s10, 0x1000
	s_addc_u32 s11, s11, 0
	v_mov_b32_e32 v43, 0x3a000000
	v_mov_b32_e32 v34, 0x358637bd
	s_waitcnt vmcnt(20)
	v_lshlrev_b32_e32 v44, 16, v100
	v_and_b32_e32 v45, 0xffff0000, v100
	v_lshlrev_b32_e32 v46, 16, v101
	v_and_b32_e32 v47, 0xffff0000, v101
	v_lshlrev_b32_e32 v48, 16, v102
	v_and_b32_e32 v49, 0xffff0000, v102
	v_lshlrev_b32_e32 v50, 16, v103
	v_and_b32_e32 v51, 0xffff0000, v103
	v_lshlrev_b32_e32 v52, 16, v104
	v_and_b32_e32 v53, 0xffff0000, v104
	v_lshlrev_b32_e32 v54, 16, v105
	v_and_b32_e32 v55, 0xffff0000, v105
	v_lshlrev_b32_e32 v56, 16, v106
	v_and_b32_e32 v57, 0xffff0000, v106
	v_lshlrev_b32_e32 v58, 16, v107
	v_and_b32_e32 v59, 0xffff0000, v107
	v_lshlrev_b32_e32 v60, 16, v108
	v_and_b32_e32 v61, 0xffff0000, v108
	v_lshlrev_b32_e32 v62, 16, v109
	v_and_b32_e32 v63, 0xffff0000, v109
	v_lshlrev_b32_e32 v64, 16, v110
	v_and_b32_e32 v65, 0xffff0000, v110
	v_lshlrev_b32_e32 v66, 16, v111
	v_and_b32_e32 v67, 0xffff0000, v111
	v_lshlrev_b32_e32 v68, 16, v112
	v_and_b32_e32 v69, 0xffff0000, v112
	v_lshlrev_b32_e32 v70, 16, v113
	v_and_b32_e32 v71, 0xffff0000, v113
	v_lshlrev_b32_e32 v72, 16, v114
	v_and_b32_e32 v73, 0xffff0000, v114
	v_lshlrev_b32_e32 v74, 16, v115
	v_and_b32_e32 v75, 0xffff0000, v115
	global_load_dwordx4 v[100:103], v36, s[10:11]
	global_load_dwordx4 v[104:107], v36, s[10:11] offset:1024
	global_load_dwordx4 v[108:111], v36, s[10:11] offset:2048
	global_load_dwordx4 v[112:115], v36, s[10:11] offset:3072
	s_add_u32 s10, s10, 0x1000
	s_addc_u32 s11, s11, 0
	v_pk_mul_f32 v[38:39], v[44:45], v[44:45]
	v_pk_fma_f32 v[38:39], v[46:47], v[46:47], v[38:39]
	v_pk_fma_f32 v[38:39], v[48:49], v[48:49], v[38:39]
	v_pk_fma_f32 v[38:39], v[50:51], v[50:51], v[38:39]
	v_pk_fma_f32 v[38:39], v[52:53], v[52:53], v[38:39]
	v_pk_fma_f32 v[38:39], v[54:55], v[54:55], v[38:39]
	v_pk_fma_f32 v[38:39], v[56:57], v[56:57], v[38:39]
	v_pk_fma_f32 v[38:39], v[58:59], v[58:59], v[38:39]
	v_pk_fma_f32 v[38:39], v[60:61], v[60:61], v[38:39]
	v_pk_fma_f32 v[38:39], v[62:63], v[62:63], v[38:39]
	v_pk_fma_f32 v[38:39], v[64:65], v[64:65], v[38:39]
	v_pk_fma_f32 v[38:39], v[66:67], v[66:67], v[38:39]
	v_pk_fma_f32 v[38:39], v[68:69], v[68:69], v[38:39]
	v_pk_fma_f32 v[38:39], v[70:71], v[70:71], v[38:39]
	v_pk_fma_f32 v[38:39], v[72:73], v[72:73], v[38:39]
	v_pk_fma_f32 v[38:39], v[74:75], v[74:75], v[38:39]
	v_add_f32_e32 v38, v38, v39
	s_nop 1
	v_add_f32_dpp v38, v38, v38 quad_perm:[1,0,3,2] row_mask:0xf bank_mask:0xf
	s_nop 1
	v_add_f32_dpp v38, v38, v38 quad_perm:[2,3,0,1] row_mask:0xf bank_mask:0xf
	s_nop 1
	v_add_f32_dpp v38, v38, v38 row_half_mirror row_mask:0xf bank_mask:0xf
	s_nop 1
	v_add_f32_dpp v38, v38, v38 row_mirror row_mask:0xf bank_mask:0xf
	s_nop 1
	v_add_f32_dpp v38, v38, v38 row_bcast:15 row_mask:0xa bank_mask:0xf
	s_nop 1
	v_add_f32_dpp v38, v38, v38 row_bcast:31 row_mask:0xc bank_mask:0xf
	s_nop 1
	v_readlane_b32 s100, v38, 63
	s_nop 3
	v_mov_b32_e32 v40, s100
	v_fma_f32 v40, v40, v43, v34
	v_rsq_f32_e32 v41, v40
	s_nop 0
	v_mul_f32_e32 v42, v40, v41
	v_mul_f32_e32 v42, v42, v41
	v_fmaak_f32 v42, -0.5, v42, 0x3fc00000
	v_mul_f32_e32 v40, v41, v42
	v_mov_b32_e32 v41, v40
	s_waitcnt vmcnt(16)
	v_pk_mul_f32 v[44:45], v[44:45], v[40:41]
	v_pk_mul_f32 v[44:45], v[44:45], v[2:3]
	v_pk_mul_f32 v[46:47], v[46:47], v[40:41]
	v_pk_mul_f32 v[46:47], v[46:47], v[4:5]
	v_pk_mul_f32 v[48:49], v[48:49], v[40:41]
	v_pk_mul_f32 v[48:49], v[48:49], v[6:7]
	v_pk_mul_f32 v[50:51], v[50:51], v[40:41]
	v_pk_mul_f32 v[50:51], v[50:51], v[8:9]
	v_pk_mul_f32 v[52:53], v[52:53], v[40:41]
	v_pk_mul_f32 v[52:53], v[52:53], v[10:11]
	v_pk_mul_f32 v[54:55], v[54:55], v[40:41]
	v_pk_mul_f32 v[54:55], v[54:55], v[12:13]
	v_pk_mul_f32 v[56:57], v[56:57], v[40:41]
	v_pk_mul_f32 v[56:57], v[56:57], v[14:15]
	v_pk_mul_f32 v[58:59], v[58:59], v[40:41]
	v_pk_mul_f32 v[58:59], v[58:59], v[16:17]
	v_pk_mul_f32 v[60:61], v[60:61], v[40:41]
	v_pk_mul_f32 v[60:61], v[60:61], v[18:19]
	v_pk_mul_f32 v[62:63], v[62:63], v[40:41]
	v_pk_mul_f32 v[62:63], v[62:63], v[20:21]
	v_pk_mul_f32 v[64:65], v[64:65], v[40:41]
	v_pk_mul_f32 v[64:65], v[64:65], v[22:23]
	v_pk_mul_f32 v[66:67], v[66:67], v[40:41]
	v_pk_mul_f32 v[66:67], v[66:67], v[24:25]
	v_pk_mul_f32 v[68:69], v[68:69], v[40:41]
	v_pk_mul_f32 v[68:69], v[68:69], v[26:27]
	v_pk_mul_f32 v[70:71], v[70:71], v[40:41]
	v_pk_mul_f32 v[70:71], v[70:71], v[28:29]
	v_pk_mul_f32 v[72:73], v[72:73], v[40:41]
	v_pk_mul_f32 v[72:73], v[72:73], v[30:31]
	v_pk_mul_f32 v[74:75], v[74:75], v[40:41]
	v_pk_mul_f32 v[74:75], v[74:75], v[32:33]
	global_store_dwordx4 v37, v[44:47], s[20:21]
	global_store_dwordx4 v37, v[48:51], s[20:21] offset:16
	global_store_dwordx4 v37, v[52:55], s[20:21] offset:2048
	global_store_dwordx4 v37, v[56:59], s[20:21] offset:2064
	s_add_u32 s20, s20, 0x1000
	s_addc_u32 s21, s21, 0
	global_store_dwordx4 v37, v[60:63], s[20:21]
	global_store_dwordx4 v37, v[64:67], s[20:21] offset:16
	global_store_dwordx4 v37, v[68:71], s[20:21] offset:2048
	global_store_dwordx4 v37, v[72:75], s[20:21] offset:2064
	s_add_u32 s20, s20, 0x1000
	s_addc_u32 s21, s21, 0
	s_waitcnt vmcnt(20)
	v_lshlrev_b32_e32 v164, 16, v116
	v_and_b32_e32 v165, 0xffff0000, v116
	v_lshlrev_b32_e32 v166, 16, v117
	v_and_b32_e32 v167, 0xffff0000, v117
	v_lshlrev_b32_e32 v168, 16, v118
	v_and_b32_e32 v169, 0xffff0000, v118
	v_lshlrev_b32_e32 v170, 16, v119
	v_and_b32_e32 v171, 0xffff0000, v119
	v_lshlrev_b32_e32 v172, 16, v120
	v_and_b32_e32 v173, 0xffff0000, v120
	v_lshlrev_b32_e32 v174, 16, v121
	v_and_b32_e32 v175, 0xffff0000, v121
	v_lshlrev_b32_e32 v176, 16, v122
	v_and_b32_e32 v177, 0xffff0000, v122
	v_lshlrev_b32_e32 v178, 16, v123
	v_and_b32_e32 v179, 0xffff0000, v123
	v_lshlrev_b32_e32 v180, 16, v124
	v_and_b32_e32 v181, 0xffff0000, v124
	v_lshlrev_b32_e32 v182, 16, v125
	v_and_b32_e32 v183, 0xffff0000, v125
	v_lshlrev_b32_e32 v184, 16, v126
	v_and_b32_e32 v185, 0xffff0000, v126
	v_lshlrev_b32_e32 v186, 16, v127
	v_and_b32_e32 v187, 0xffff0000, v127
	v_lshlrev_b32_e32 v188, 16, v128
	v_and_b32_e32 v189, 0xffff0000, v128
	v_lshlrev_b32_e32 v190, 16, v129
	v_and_b32_e32 v191, 0xffff0000, v129
	v_lshlrev_b32_e32 v192, 16, v130
	v_and_b32_e32 v193, 0xffff0000, v130
	v_lshlrev_b32_e32 v194, 16, v131
	v_and_b32_e32 v195, 0xffff0000, v131
	global_load_dwordx4 v[116:119], v36, s[10:11]
	global_load_dwordx4 v[120:123], v36, s[10:11] offset:1024
	global_load_dwordx4 v[124:127], v36, s[10:11] offset:2048
	global_load_dwordx4 v[128:131], v36, s[10:11] offset:3072
	s_add_u32 s10, s10, 0x1000
	s_addc_u32 s11, s11, 0
	v_pk_mul_f32 v[38:39], v[164:165], v[164:165]
	v_pk_fma_f32 v[38:39], v[166:167], v[166:167], v[38:39]
	v_pk_fma_f32 v[38:39], v[168:169], v[168:169], v[38:39]
	v_pk_fma_f32 v[38:39], v[170:171], v[170:171], v[38:39]
	v_pk_fma_f32 v[38:39], v[172:173], v[172:173], v[38:39]
	v_pk_fma_f32 v[38:39], v[174:175], v[174:175], v[38:39]
	v_pk_fma_f32 v[38:39], v[176:177], v[176:177], v[38:39]
	v_pk_fma_f32 v[38:39], v[178:179], v[178:179], v[38:39]
	v_pk_fma_f32 v[38:39], v[180:181], v[180:181], v[38:39]
	v_pk_fma_f32 v[38:39], v[182:183], v[182:183], v[38:39]
	v_pk_fma_f32 v[38:39], v[184:185], v[184:185], v[38:39]
	v_pk_fma_f32 v[38:39], v[186:187], v[186:187], v[38:39]
	v_pk_fma_f32 v[38:39], v[188:189], v[188:189], v[38:39]
	v_pk_fma_f32 v[38:39], v[190:191], v[190:191], v[38:39]
	v_pk_fma_f32 v[38:39], v[192:193], v[192:193], v[38:39]
	v_pk_fma_f32 v[38:39], v[194:195], v[194:195], v[38:39]
	v_add_f32_e32 v38, v38, v39
	s_nop 1
	v_add_f32_dpp v38, v38, v38 quad_perm:[1,0,3,2] row_mask:0xf bank_mask:0xf
	s_nop 1
	v_add_f32_dpp v38, v38, v38 quad_perm:[2,3,0,1] row_mask:0xf bank_mask:0xf
	s_nop 1
	v_add_f32_dpp v38, v38, v38 row_half_mirror row_mask:0xf bank_mask:0xf
	s_nop 1
	v_add_f32_dpp v38, v38, v38 row_mirror row_mask:0xf bank_mask:0xf
	s_nop 1
	v_add_f32_dpp v38, v38, v38 row_bcast:15 row_mask:0xa bank_mask:0xf
	s_nop 1
	v_add_f32_dpp v38, v38, v38 row_bcast:31 row_mask:0xc bank_mask:0xf
	s_nop 1
	v_readlane_b32 s100, v38, 63
	s_nop 3
	v_mov_b32_e32 v40, s100
	v_fma_f32 v40, v40, v43, v34
	v_rsq_f32_e32 v41, v40
	s_nop 0
	v_mul_f32_e32 v42, v40, v41
	v_mul_f32_e32 v42, v42, v41
	v_fmaak_f32 v42, -0.5, v42, 0x3fc00000
	v_mul_f32_e32 v40, v41, v42
	v_mov_b32_e32 v41, v40
	v_pk_mul_f32 v[164:165], v[164:165], v[40:41]
	v_pk_mul_f32 v[164:165], v[164:165], v[2:3]
	v_pk_mul_f32 v[166:167], v[166:167], v[40:41]
	v_pk_mul_f32 v[166:167], v[166:167], v[4:5]
	v_pk_mul_f32 v[168:169], v[168:169], v[40:41]
	v_pk_mul_f32 v[168:169], v[168:169], v[6:7]
	v_pk_mul_f32 v[170:171], v[170:171], v[40:41]
	v_pk_mul_f32 v[170:171], v[170:171], v[8:9]
	v_pk_mul_f32 v[172:173], v[172:173], v[40:41]
	v_pk_mul_f32 v[172:173], v[172:173], v[10:11]
	v_pk_mul_f32 v[174:175], v[174:175], v[40:41]
	v_pk_mul_f32 v[174:175], v[174:175], v[12:13]
	v_pk_mul_f32 v[176:177], v[176:177], v[40:41]
	v_pk_mul_f32 v[176:177], v[176:177], v[14:15]
	v_pk_mul_f32 v[178:179], v[178:179], v[40:41]
	v_pk_mul_f32 v[178:179], v[178:179], v[16:17]
	v_pk_mul_f32 v[180:181], v[180:181], v[40:41]
	v_pk_mul_f32 v[180:181], v[180:181], v[18:19]
	v_pk_mul_f32 v[182:183], v[182:183], v[40:41]
	v_pk_mul_f32 v[182:183], v[182:183], v[20:21]
	v_pk_mul_f32 v[184:185], v[184:185], v[40:41]
	v_pk_mul_f32 v[184:185], v[184:185], v[22:23]
	v_pk_mul_f32 v[186:187], v[186:187], v[40:41]
	v_pk_mul_f32 v[186:187], v[186:187], v[24:25]
	v_pk_mul_f32 v[188:189], v[188:189], v[40:41]
	v_pk_mul_f32 v[188:189], v[188:189], v[26:27]
	v_pk_mul_f32 v[190:191], v[190:191], v[40:41]
	v_pk_mul_f32 v[190:191], v[190:191], v[28:29]
	v_pk_mul_f32 v[192:193], v[192:193], v[40:41]
	v_pk_mul_f32 v[192:193], v[192:193], v[30:31]
	v_pk_mul_f32 v[194:195], v[194:195], v[40:41]
	v_pk_mul_f32 v[194:195], v[194:195], v[32:33]
	global_store_dwordx4 v37, v[164:167], s[20:21]
	global_store_dwordx4 v37, v[168:171], s[20:21] offset:16
	global_store_dwordx4 v37, v[172:175], s[20:21] offset:2048
	global_store_dwordx4 v37, v[176:179], s[20:21] offset:2064
	s_add_u32 s20, s20, 0x1000
	s_addc_u32 s21, s21, 0
	global_store_dwordx4 v37, v[180:183], s[20:21]
	global_store_dwordx4 v37, v[184:187], s[20:21] offset:16
	global_store_dwordx4 v37, v[188:191], s[20:21] offset:2048
	global_store_dwordx4 v37, v[192:195], s[20:21] offset:2064
	s_add_u32 s20, s20, 0x1000
	s_addc_u32 s21, s21, 0
	s_waitcnt vmcnt(28)
	v_lshlrev_b32_e32 v44, 16, v132
	v_and_b32_e32 v45, 0xffff0000, v132
	v_lshlrev_b32_e32 v46, 16, v133
	v_and_b32_e32 v47, 0xffff0000, v133
	v_lshlrev_b32_e32 v48, 16, v134
	v_and_b32_e32 v49, 0xffff0000, v134
	v_lshlrev_b32_e32 v50, 16, v135
	v_and_b32_e32 v51, 0xffff0000, v135
	v_lshlrev_b32_e32 v52, 16, v136
	v_and_b32_e32 v53, 0xffff0000, v136
	v_lshlrev_b32_e32 v54, 16, v137
	v_and_b32_e32 v55, 0xffff0000, v137
	v_lshlrev_b32_e32 v56, 16, v138
	v_and_b32_e32 v57, 0xffff0000, v138
	v_lshlrev_b32_e32 v58, 16, v139
	v_and_b32_e32 v59, 0xffff0000, v139
	v_lshlrev_b32_e32 v60, 16, v140
	v_and_b32_e32 v61, 0xffff0000, v140
	v_lshlrev_b32_e32 v62, 16, v141
	v_and_b32_e32 v63, 0xffff0000, v141
	v_lshlrev_b32_e32 v64, 16, v142
	v_and_b32_e32 v65, 0xffff0000, v142
	v_lshlrev_b32_e32 v66, 16, v143
	v_and_b32_e32 v67, 0xffff0000, v143
	v_lshlrev_b32_e32 v68, 16, v144
	v_and_b32_e32 v69, 0xffff0000, v144
	v_lshlrev_b32_e32 v70, 16, v145
	v_and_b32_e32 v71, 0xffff0000, v145
	v_lshlrev_b32_e32 v72, 16, v146
	v_and_b32_e32 v73, 0xffff0000, v146
	v_lshlrev_b32_e32 v74, 16, v147
	v_and_b32_e32 v75, 0xffff0000, v147
	global_load_dwordx4 v[132:135], v36, s[10:11]
	global_load_dwordx4 v[136:139], v36, s[10:11] offset:1024
	global_load_dwordx4 v[140:143], v36, s[10:11] offset:2048
	global_load_dwordx4 v[144:147], v36, s[10:11] offset:3072
	s_add_u32 s10, s10, 0x1000
	s_addc_u32 s11, s11, 0
	v_pk_mul_f32 v[38:39], v[44:45], v[44:45]
	v_pk_fma_f32 v[38:39], v[46:47], v[46:47], v[38:39]
	v_pk_fma_f32 v[38:39], v[48:49], v[48:49], v[38:39]
	v_pk_fma_f32 v[38:39], v[50:51], v[50:51], v[38:39]
	v_pk_fma_f32 v[38:39], v[52:53], v[52:53], v[38:39]
	v_pk_fma_f32 v[38:39], v[54:55], v[54:55], v[38:39]
	v_pk_fma_f32 v[38:39], v[56:57], v[56:57], v[38:39]
	v_pk_fma_f32 v[38:39], v[58:59], v[58:59], v[38:39]
	v_pk_fma_f32 v[38:39], v[60:61], v[60:61], v[38:39]
	v_pk_fma_f32 v[38:39], v[62:63], v[62:63], v[38:39]
	v_pk_fma_f32 v[38:39], v[64:65], v[64:65], v[38:39]
	v_pk_fma_f32 v[38:39], v[66:67], v[66:67], v[38:39]
	v_pk_fma_f32 v[38:39], v[68:69], v[68:69], v[38:39]
	v_pk_fma_f32 v[38:39], v[70:71], v[70:71], v[38:39]
	v_pk_fma_f32 v[38:39], v[72:73], v[72:73], v[38:39]
	v_pk_fma_f32 v[38:39], v[74:75], v[74:75], v[38:39]
	v_add_f32_e32 v38, v38, v39
	s_nop 1
	v_add_f32_dpp v38, v38, v38 quad_perm:[1,0,3,2] row_mask:0xf bank_mask:0xf
	s_nop 1
	v_add_f32_dpp v38, v38, v38 quad_perm:[2,3,0,1] row_mask:0xf bank_mask:0xf
	s_nop 1
	v_add_f32_dpp v38, v38, v38 row_half_mirror row_mask:0xf bank_mask:0xf
	s_nop 1
	v_add_f32_dpp v38, v38, v38 row_mirror row_mask:0xf bank_mask:0xf
	s_nop 1
	v_add_f32_dpp v38, v38, v38 row_bcast:15 row_mask:0xa bank_mask:0xf
	s_nop 1
	v_add_f32_dpp v38, v38, v38 row_bcast:31 row_mask:0xc bank_mask:0xf
	s_nop 1
	v_readlane_b32 s100, v38, 63
	s_nop 3
	v_mov_b32_e32 v40, s100
	v_fma_f32 v40, v40, v43, v34
	v_rsq_f32_e32 v41, v40
	s_nop 0
	v_mul_f32_e32 v42, v40, v41
	v_mul_f32_e32 v42, v42, v41
	v_fmaak_f32 v42, -0.5, v42, 0x3fc00000
	v_mul_f32_e32 v40, v41, v42
	v_mov_b32_e32 v41, v40
	v_pk_mul_f32 v[44:45], v[44:45], v[40:41]
	v_pk_mul_f32 v[44:45], v[44:45], v[2:3]
	v_pk_mul_f32 v[46:47], v[46:47], v[40:41]
	v_pk_mul_f32 v[46:47], v[46:47], v[4:5]
	v_pk_mul_f32 v[48:49], v[48:49], v[40:41]
	v_pk_mul_f32 v[48:49], v[48:49], v[6:7]
	v_pk_mul_f32 v[50:51], v[50:51], v[40:41]
	v_pk_mul_f32 v[50:51], v[50:51], v[8:9]
	v_pk_mul_f32 v[52:53], v[52:53], v[40:41]
	v_pk_mul_f32 v[52:53], v[52:53], v[10:11]
	v_pk_mul_f32 v[54:55], v[54:55], v[40:41]
	v_pk_mul_f32 v[54:55], v[54:55], v[12:13]
	v_pk_mul_f32 v[56:57], v[56:57], v[40:41]
	v_pk_mul_f32 v[56:57], v[56:57], v[14:15]
	v_pk_mul_f32 v[58:59], v[58:59], v[40:41]
	v_pk_mul_f32 v[58:59], v[58:59], v[16:17]
	v_pk_mul_f32 v[60:61], v[60:61], v[40:41]
	v_pk_mul_f32 v[60:61], v[60:61], v[18:19]
	v_pk_mul_f32 v[62:63], v[62:63], v[40:41]
	v_pk_mul_f32 v[62:63], v[62:63], v[20:21]
	v_pk_mul_f32 v[64:65], v[64:65], v[40:41]
	v_pk_mul_f32 v[64:65], v[64:65], v[22:23]
	v_pk_mul_f32 v[66:67], v[66:67], v[40:41]
	v_pk_mul_f32 v[66:67], v[66:67], v[24:25]
	v_pk_mul_f32 v[68:69], v[68:69], v[40:41]
	v_pk_mul_f32 v[68:69], v[68:69], v[26:27]
	v_pk_mul_f32 v[70:71], v[70:71], v[40:41]
	v_pk_mul_f32 v[70:71], v[70:71], v[28:29]
	v_pk_mul_f32 v[72:73], v[72:73], v[40:41]
	v_pk_mul_f32 v[72:73], v[72:73], v[30:31]
	v_pk_mul_f32 v[74:75], v[74:75], v[40:41]
	v_pk_mul_f32 v[74:75], v[74:75], v[32:33]
	global_store_dwordx4 v37, v[44:47], s[20:21]
	global_store_dwordx4 v37, v[48:51], s[20:21] offset:16
	global_store_dwordx4 v37, v[52:55], s[20:21] offset:2048
	global_store_dwordx4 v37, v[56:59], s[20:21] offset:2064
	s_add_u32 s20, s20, 0x1000
	s_addc_u32 s21, s21, 0
	global_store_dwordx4 v37, v[60:63], s[20:21]
	global_store_dwordx4 v37, v[64:67], s[20:21] offset:16
	global_store_dwordx4 v37, v[68:71], s[20:21] offset:2048
	global_store_dwordx4 v37, v[72:75], s[20:21] offset:2064
	s_add_u32 s20, s20, 0x1000
	s_addc_u32 s21, s21, 0
	s_waitcnt vmcnt(36)
	v_lshlrev_b32_e32 v164, 16, v148
	v_and_b32_e32 v165, 0xffff0000, v148
	v_lshlrev_b32_e32 v166, 16, v149
	v_and_b32_e32 v167, 0xffff0000, v149
	v_lshlrev_b32_e32 v168, 16, v150
	v_and_b32_e32 v169, 0xffff0000, v150
	v_lshlrev_b32_e32 v170, 16, v151
	v_and_b32_e32 v171, 0xffff0000, v151
	v_lshlrev_b32_e32 v172, 16, v152
	v_and_b32_e32 v173, 0xffff0000, v152
	v_lshlrev_b32_e32 v174, 16, v153
	v_and_b32_e32 v175, 0xffff0000, v153
	v_lshlrev_b32_e32 v176, 16, v154
	v_and_b32_e32 v177, 0xffff0000, v154
	v_lshlrev_b32_e32 v178, 16, v155
	v_and_b32_e32 v179, 0xffff0000, v155
	v_lshlrev_b32_e32 v180, 16, v156
	v_and_b32_e32 v181, 0xffff0000, v156
	v_lshlrev_b32_e32 v182, 16, v157
	v_and_b32_e32 v183, 0xffff0000, v157
	v_lshlrev_b32_e32 v184, 16, v158
	v_and_b32_e32 v185, 0xffff0000, v158
	v_lshlrev_b32_e32 v186, 16, v159
	v_and_b32_e32 v187, 0xffff0000, v159
	v_lshlrev_b32_e32 v188, 16, v160
	v_and_b32_e32 v189, 0xffff0000, v160
	v_lshlrev_b32_e32 v190, 16, v161
	v_and_b32_e32 v191, 0xffff0000, v161
	v_lshlrev_b32_e32 v192, 16, v162
	v_and_b32_e32 v193, 0xffff0000, v162
	v_lshlrev_b32_e32 v194, 16, v163
	v_and_b32_e32 v195, 0xffff0000, v163
	global_load_dwordx4 v[148:151], v36, s[10:11]
	global_load_dwordx4 v[152:155], v36, s[10:11] offset:1024
	global_load_dwordx4 v[156:159], v36, s[10:11] offset:2048
	global_load_dwordx4 v[160:163], v36, s[10:11] offset:3072
	s_add_u32 s10, s10, 0x1000
	s_addc_u32 s11, s11, 0
	v_pk_mul_f32 v[38:39], v[164:165], v[164:165]
	v_pk_fma_f32 v[38:39], v[166:167], v[166:167], v[38:39]
	v_pk_fma_f32 v[38:39], v[168:169], v[168:169], v[38:39]
	v_pk_fma_f32 v[38:39], v[170:171], v[170:171], v[38:39]
	v_pk_fma_f32 v[38:39], v[172:173], v[172:173], v[38:39]
	v_pk_fma_f32 v[38:39], v[174:175], v[174:175], v[38:39]
	v_pk_fma_f32 v[38:39], v[176:177], v[176:177], v[38:39]
	v_pk_fma_f32 v[38:39], v[178:179], v[178:179], v[38:39]
	v_pk_fma_f32 v[38:39], v[180:181], v[180:181], v[38:39]
	v_pk_fma_f32 v[38:39], v[182:183], v[182:183], v[38:39]
	v_pk_fma_f32 v[38:39], v[184:185], v[184:185], v[38:39]
	v_pk_fma_f32 v[38:39], v[186:187], v[186:187], v[38:39]
	v_pk_fma_f32 v[38:39], v[188:189], v[188:189], v[38:39]
	v_pk_fma_f32 v[38:39], v[190:191], v[190:191], v[38:39]
	v_pk_fma_f32 v[38:39], v[192:193], v[192:193], v[38:39]
	v_pk_fma_f32 v[38:39], v[194:195], v[194:195], v[38:39]
	v_add_f32_e32 v38, v38, v39
	s_nop 1
	v_add_f32_dpp v38, v38, v38 quad_perm:[1,0,3,2] row_mask:0xf bank_mask:0xf
	s_nop 1
	v_add_f32_dpp v38, v38, v38 quad_perm:[2,3,0,1] row_mask:0xf bank_mask:0xf
	s_nop 1
	v_add_f32_dpp v38, v38, v38 row_half_mirror row_mask:0xf bank_mask:0xf
	s_nop 1
	v_add_f32_dpp v38, v38, v38 row_mirror row_mask:0xf bank_mask:0xf
	s_nop 1
	v_add_f32_dpp v38, v38, v38 row_bcast:15 row_mask:0xa bank_mask:0xf
	s_nop 1
	v_add_f32_dpp v38, v38, v38 row_bcast:31 row_mask:0xc bank_mask:0xf
	s_nop 1
	v_readlane_b32 s100, v38, 63
	s_nop 3
	v_mov_b32_e32 v40, s100
	v_fma_f32 v40, v40, v43, v34
	v_rsq_f32_e32 v41, v40
	s_nop 0
	v_mul_f32_e32 v42, v40, v41
	v_mul_f32_e32 v42, v42, v41
	v_fmaak_f32 v42, -0.5, v42, 0x3fc00000
	v_mul_f32_e32 v40, v41, v42
	v_mov_b32_e32 v41, v40
	v_pk_mul_f32 v[164:165], v[164:165], v[40:41]
	v_pk_mul_f32 v[164:165], v[164:165], v[2:3]
	v_pk_mul_f32 v[166:167], v[166:167], v[40:41]
	v_pk_mul_f32 v[166:167], v[166:167], v[4:5]
	v_pk_mul_f32 v[168:169], v[168:169], v[40:41]
	v_pk_mul_f32 v[168:169], v[168:169], v[6:7]
	v_pk_mul_f32 v[170:171], v[170:171], v[40:41]
	v_pk_mul_f32 v[170:171], v[170:171], v[8:9]
	v_pk_mul_f32 v[172:173], v[172:173], v[40:41]
	v_pk_mul_f32 v[172:173], v[172:173], v[10:11]
	v_pk_mul_f32 v[174:175], v[174:175], v[40:41]
	v_pk_mul_f32 v[174:175], v[174:175], v[12:13]
	v_pk_mul_f32 v[176:177], v[176:177], v[40:41]
	v_pk_mul_f32 v[176:177], v[176:177], v[14:15]
	v_pk_mul_f32 v[178:179], v[178:179], v[40:41]
	v_pk_mul_f32 v[178:179], v[178:179], v[16:17]
	v_pk_mul_f32 v[180:181], v[180:181], v[40:41]
	v_pk_mul_f32 v[180:181], v[180:181], v[18:19]
	v_pk_mul_f32 v[182:183], v[182:183], v[40:41]
	v_pk_mul_f32 v[182:183], v[182:183], v[20:21]
	v_pk_mul_f32 v[184:185], v[184:185], v[40:41]
	v_pk_mul_f32 v[184:185], v[184:185], v[22:23]
	v_pk_mul_f32 v[186:187], v[186:187], v[40:41]
	v_pk_mul_f32 v[186:187], v[186:187], v[24:25]
	v_pk_mul_f32 v[188:189], v[188:189], v[40:41]
	v_pk_mul_f32 v[188:189], v[188:189], v[26:27]
	v_pk_mul_f32 v[190:191], v[190:191], v[40:41]
	v_pk_mul_f32 v[190:191], v[190:191], v[28:29]
	v_pk_mul_f32 v[192:193], v[192:193], v[40:41]
	v_pk_mul_f32 v[192:193], v[192:193], v[30:31]
	v_pk_mul_f32 v[194:195], v[194:195], v[40:41]
	v_pk_mul_f32 v[194:195], v[194:195], v[32:33]
	global_store_dwordx4 v37, v[164:167], s[20:21]
	global_store_dwordx4 v37, v[168:171], s[20:21] offset:16
	global_store_dwordx4 v37, v[172:175], s[20:21] offset:2048
	global_store_dwordx4 v37, v[176:179], s[20:21] offset:2064
	s_add_u32 s20, s20, 0x1000
	s_addc_u32 s21, s21, 0
	global_store_dwordx4 v37, v[180:183], s[20:21]
	global_store_dwordx4 v37, v[184:187], s[20:21] offset:16
	global_store_dwordx4 v37, v[188:191], s[20:21] offset:2048
	global_store_dwordx4 v37, v[192:195], s[20:21] offset:2064
	s_add_u32 s20, s20, 0x1000
	s_addc_u32 s21, s21, 0
	s_waitcnt vmcnt(44)
	v_lshlrev_b32_e32 v44, 16, v100
	v_and_b32_e32 v45, 0xffff0000, v100
	v_lshlrev_b32_e32 v46, 16, v101
	v_and_b32_e32 v47, 0xffff0000, v101
	v_lshlrev_b32_e32 v48, 16, v102
	v_and_b32_e32 v49, 0xffff0000, v102
	v_lshlrev_b32_e32 v50, 16, v103
	v_and_b32_e32 v51, 0xffff0000, v103
	v_lshlrev_b32_e32 v52, 16, v104
	v_and_b32_e32 v53, 0xffff0000, v104
	v_lshlrev_b32_e32 v54, 16, v105
	v_and_b32_e32 v55, 0xffff0000, v105
	v_lshlrev_b32_e32 v56, 16, v106
	v_and_b32_e32 v57, 0xffff0000, v106
	v_lshlrev_b32_e32 v58, 16, v107
	v_and_b32_e32 v59, 0xffff0000, v107
	v_lshlrev_b32_e32 v60, 16, v108
	v_and_b32_e32 v61, 0xffff0000, v108
	v_lshlrev_b32_e32 v62, 16, v109
	v_and_b32_e32 v63, 0xffff0000, v109
	v_lshlrev_b32_e32 v64, 16, v110
	v_and_b32_e32 v65, 0xffff0000, v110
	v_lshlrev_b32_e32 v66, 16, v111
	v_and_b32_e32 v67, 0xffff0000, v111
	v_lshlrev_b32_e32 v68, 16, v112
	v_and_b32_e32 v69, 0xffff0000, v112
	v_lshlrev_b32_e32 v70, 16, v113
	v_and_b32_e32 v71, 0xffff0000, v113
	v_lshlrev_b32_e32 v72, 16, v114
	v_and_b32_e32 v73, 0xffff0000, v114
	v_lshlrev_b32_e32 v74, 16, v115
	v_and_b32_e32 v75, 0xffff0000, v115
	v_pk_mul_f32 v[38:39], v[44:45], v[44:45]
	v_pk_fma_f32 v[38:39], v[46:47], v[46:47], v[38:39]
	v_pk_fma_f32 v[38:39], v[48:49], v[48:49], v[38:39]
	v_pk_fma_f32 v[38:39], v[50:51], v[50:51], v[38:39]
	v_pk_fma_f32 v[38:39], v[52:53], v[52:53], v[38:39]
	v_pk_fma_f32 v[38:39], v[54:55], v[54:55], v[38:39]
	v_pk_fma_f32 v[38:39], v[56:57], v[56:57], v[38:39]
	v_pk_fma_f32 v[38:39], v[58:59], v[58:59], v[38:39]
	v_pk_fma_f32 v[38:39], v[60:61], v[60:61], v[38:39]
	v_pk_fma_f32 v[38:39], v[62:63], v[62:63], v[38:39]
	v_pk_fma_f32 v[38:39], v[64:65], v[64:65], v[38:39]
	v_pk_fma_f32 v[38:39], v[66:67], v[66:67], v[38:39]
	v_pk_fma_f32 v[38:39], v[68:69], v[68:69], v[38:39]
	v_pk_fma_f32 v[38:39], v[70:71], v[70:71], v[38:39]
	v_pk_fma_f32 v[38:39], v[72:73], v[72:73], v[38:39]
	v_pk_fma_f32 v[38:39], v[74:75], v[74:75], v[38:39]
	v_add_f32_e32 v38, v38, v39
	s_nop 1
	v_add_f32_dpp v38, v38, v38 quad_perm:[1,0,3,2] row_mask:0xf bank_mask:0xf
	s_nop 1
	v_add_f32_dpp v38, v38, v38 quad_perm:[2,3,0,1] row_mask:0xf bank_mask:0xf
	s_nop 1
	v_add_f32_dpp v38, v38, v38 row_half_mirror row_mask:0xf bank_mask:0xf
	s_nop 1
	v_add_f32_dpp v38, v38, v38 row_mirror row_mask:0xf bank_mask:0xf
	s_nop 1
	v_add_f32_dpp v38, v38, v38 row_bcast:15 row_mask:0xa bank_mask:0xf
	s_nop 1
	v_add_f32_dpp v38, v38, v38 row_bcast:31 row_mask:0xc bank_mask:0xf
	s_nop 1
	v_readlane_b32 s100, v38, 63
	s_nop 3
	v_mov_b32_e32 v40, s100
	v_fma_f32 v40, v40, v43, v34
	v_rsq_f32_e32 v41, v40
	s_nop 0
	v_mul_f32_e32 v42, v40, v41
	v_mul_f32_e32 v42, v42, v41
	v_fmaak_f32 v42, -0.5, v42, 0x3fc00000
	v_mul_f32_e32 v40, v41, v42
	v_mov_b32_e32 v41, v40
	v_pk_mul_f32 v[44:45], v[44:45], v[40:41]
	v_pk_mul_f32 v[44:45], v[44:45], v[2:3]
	v_pk_mul_f32 v[46:47], v[46:47], v[40:41]
	v_pk_mul_f32 v[46:47], v[46:47], v[4:5]
	v_pk_mul_f32 v[48:49], v[48:49], v[40:41]
	v_pk_mul_f32 v[48:49], v[48:49], v[6:7]
	v_pk_mul_f32 v[50:51], v[50:51], v[40:41]
	v_pk_mul_f32 v[50:51], v[50:51], v[8:9]
	v_pk_mul_f32 v[52:53], v[52:53], v[40:41]
	v_pk_mul_f32 v[52:53], v[52:53], v[10:11]
	v_pk_mul_f32 v[54:55], v[54:55], v[40:41]
	v_pk_mul_f32 v[54:55], v[54:55], v[12:13]
	v_pk_mul_f32 v[56:57], v[56:57], v[40:41]
	v_pk_mul_f32 v[56:57], v[56:57], v[14:15]
	v_pk_mul_f32 v[58:59], v[58:59], v[40:41]
	v_pk_mul_f32 v[58:59], v[58:59], v[16:17]
	v_pk_mul_f32 v[60:61], v[60:61], v[40:41]
	v_pk_mul_f32 v[60:61], v[60:61], v[18:19]
	v_pk_mul_f32 v[62:63], v[62:63], v[40:41]
	v_pk_mul_f32 v[62:63], v[62:63], v[20:21]
	v_pk_mul_f32 v[64:65], v[64:65], v[40:41]
	v_pk_mul_f32 v[64:65], v[64:65], v[22:23]
	v_pk_mul_f32 v[66:67], v[66:67], v[40:41]
	v_pk_mul_f32 v[66:67], v[66:67], v[24:25]
	v_pk_mul_f32 v[68:69], v[68:69], v[40:41]
	v_pk_mul_f32 v[68:69], v[68:69], v[26:27]
	v_pk_mul_f32 v[70:71], v[70:71], v[40:41]
	v_pk_mul_f32 v[70:71], v[70:71], v[28:29]
	v_pk_mul_f32 v[72:73], v[72:73], v[40:41]
	v_pk_mul_f32 v[72:73], v[72:73], v[30:31]
	v_pk_mul_f32 v[74:75], v[74:75], v[40:41]
	v_pk_mul_f32 v[74:75], v[74:75], v[32:33]
	global_store_dwordx4 v37, v[44:47], s[20:21]
	global_store_dwordx4 v37, v[48:51], s[20:21] offset:16
	global_store_dwordx4 v37, v[52:55], s[20:21] offset:2048
	global_store_dwordx4 v37, v[56:59], s[20:21] offset:2064
	s_add_u32 s20, s20, 0x1000
	s_addc_u32 s21, s21, 0
	global_store_dwordx4 v37, v[60:63], s[20:21]
	global_store_dwordx4 v37, v[64:67], s[20:21] offset:16
	global_store_dwordx4 v37, v[68:71], s[20:21] offset:2048
	global_store_dwordx4 v37, v[72:75], s[20:21] offset:2064
	s_add_u32 s20, s20, 0x1000
	s_addc_u32 s21, s21, 0
	s_waitcnt vmcnt(40)
	v_lshlrev_b32_e32 v164, 16, v116
	v_and_b32_e32 v165, 0xffff0000, v116
	v_lshlrev_b32_e32 v166, 16, v117
	v_and_b32_e32 v167, 0xffff0000, v117
	v_lshlrev_b32_e32 v168, 16, v118
	v_and_b32_e32 v169, 0xffff0000, v118
	v_lshlrev_b32_e32 v170, 16, v119
	v_and_b32_e32 v171, 0xffff0000, v119
	v_lshlrev_b32_e32 v172, 16, v120
	v_and_b32_e32 v173, 0xffff0000, v120
	v_lshlrev_b32_e32 v174, 16, v121
	v_and_b32_e32 v175, 0xffff0000, v121
	v_lshlrev_b32_e32 v176, 16, v122
	v_and_b32_e32 v177, 0xffff0000, v122
	v_lshlrev_b32_e32 v178, 16, v123
	v_and_b32_e32 v179, 0xffff0000, v123
	v_lshlrev_b32_e32 v180, 16, v124
	v_and_b32_e32 v181, 0xffff0000, v124
	v_lshlrev_b32_e32 v182, 16, v125
	v_and_b32_e32 v183, 0xffff0000, v125
	v_lshlrev_b32_e32 v184, 16, v126
	v_and_b32_e32 v185, 0xffff0000, v126
	v_lshlrev_b32_e32 v186, 16, v127
	v_and_b32_e32 v187, 0xffff0000, v127
	v_lshlrev_b32_e32 v188, 16, v128
	v_and_b32_e32 v189, 0xffff0000, v128
	v_lshlrev_b32_e32 v190, 16, v129
	v_and_b32_e32 v191, 0xffff0000, v129
	v_lshlrev_b32_e32 v192, 16, v130
	v_and_b32_e32 v193, 0xffff0000, v130
	v_lshlrev_b32_e32 v194, 16, v131
	v_and_b32_e32 v195, 0xffff0000, v131
	v_pk_mul_f32 v[38:39], v[164:165], v[164:165]
	v_pk_fma_f32 v[38:39], v[166:167], v[166:167], v[38:39]
	v_pk_fma_f32 v[38:39], v[168:169], v[168:169], v[38:39]
	v_pk_fma_f32 v[38:39], v[170:171], v[170:171], v[38:39]
	v_pk_fma_f32 v[38:39], v[172:173], v[172:173], v[38:39]
	v_pk_fma_f32 v[38:39], v[174:175], v[174:175], v[38:39]
	v_pk_fma_f32 v[38:39], v[176:177], v[176:177], v[38:39]
	v_pk_fma_f32 v[38:39], v[178:179], v[178:179], v[38:39]
	v_pk_fma_f32 v[38:39], v[180:181], v[180:181], v[38:39]
	v_pk_fma_f32 v[38:39], v[182:183], v[182:183], v[38:39]
	v_pk_fma_f32 v[38:39], v[184:185], v[184:185], v[38:39]
	v_pk_fma_f32 v[38:39], v[186:187], v[186:187], v[38:39]
	v_pk_fma_f32 v[38:39], v[188:189], v[188:189], v[38:39]
	v_pk_fma_f32 v[38:39], v[190:191], v[190:191], v[38:39]
	v_pk_fma_f32 v[38:39], v[192:193], v[192:193], v[38:39]
	v_pk_fma_f32 v[38:39], v[194:195], v[194:195], v[38:39]
	v_add_f32_e32 v38, v38, v39
	s_nop 1
	v_add_f32_dpp v38, v38, v38 quad_perm:[1,0,3,2] row_mask:0xf bank_mask:0xf
	s_nop 1
	v_add_f32_dpp v38, v38, v38 quad_perm:[2,3,0,1] row_mask:0xf bank_mask:0xf
	s_nop 1
	v_add_f32_dpp v38, v38, v38 row_half_mirror row_mask:0xf bank_mask:0xf
	s_nop 1
	v_add_f32_dpp v38, v38, v38 row_mirror row_mask:0xf bank_mask:0xf
	s_nop 1
	v_add_f32_dpp v38, v38, v38 row_bcast:15 row_mask:0xa bank_mask:0xf
	s_nop 1
	v_add_f32_dpp v38, v38, v38 row_bcast:31 row_mask:0xc bank_mask:0xf
	s_nop 1
	v_readlane_b32 s100, v38, 63
	s_nop 3
	v_mov_b32_e32 v40, s100
	v_fma_f32 v40, v40, v43, v34
	v_rsq_f32_e32 v41, v40
	s_nop 0
	v_mul_f32_e32 v42, v40, v41
	v_mul_f32_e32 v42, v42, v41
	v_fmaak_f32 v42, -0.5, v42, 0x3fc00000
	v_mul_f32_e32 v40, v41, v42
	v_mov_b32_e32 v41, v40
	v_pk_mul_f32 v[164:165], v[164:165], v[40:41]
	v_pk_mul_f32 v[164:165], v[164:165], v[2:3]
	v_pk_mul_f32 v[166:167], v[166:167], v[40:41]
	v_pk_mul_f32 v[166:167], v[166:167], v[4:5]
	v_pk_mul_f32 v[168:169], v[168:169], v[40:41]
	v_pk_mul_f32 v[168:169], v[168:169], v[6:7]
	v_pk_mul_f32 v[170:171], v[170:171], v[40:41]
	v_pk_mul_f32 v[170:171], v[170:171], v[8:9]
	v_pk_mul_f32 v[172:173], v[172:173], v[40:41]
	v_pk_mul_f32 v[172:173], v[172:173], v[10:11]
	v_pk_mul_f32 v[174:175], v[174:175], v[40:41]
	v_pk_mul_f32 v[174:175], v[174:175], v[12:13]
	v_pk_mul_f32 v[176:177], v[176:177], v[40:41]
	v_pk_mul_f32 v[176:177], v[176:177], v[14:15]
	v_pk_mul_f32 v[178:179], v[178:179], v[40:41]
	v_pk_mul_f32 v[178:179], v[178:179], v[16:17]
	v_pk_mul_f32 v[180:181], v[180:181], v[40:41]
	v_pk_mul_f32 v[180:181], v[180:181], v[18:19]
	v_pk_mul_f32 v[182:183], v[182:183], v[40:41]
	v_pk_mul_f32 v[182:183], v[182:183], v[20:21]
	v_pk_mul_f32 v[184:185], v[184:185], v[40:41]
	v_pk_mul_f32 v[184:185], v[184:185], v[22:23]
	v_pk_mul_f32 v[186:187], v[186:187], v[40:41]
	v_pk_mul_f32 v[186:187], v[186:187], v[24:25]
	v_pk_mul_f32 v[188:189], v[188:189], v[40:41]
	v_pk_mul_f32 v[188:189], v[188:189], v[26:27]
	v_pk_mul_f32 v[190:191], v[190:191], v[40:41]
	v_pk_mul_f32 v[190:191], v[190:191], v[28:29]
	v_pk_mul_f32 v[192:193], v[192:193], v[40:41]
	v_pk_mul_f32 v[192:193], v[192:193], v[30:31]
	v_pk_mul_f32 v[194:195], v[194:195], v[40:41]
	v_pk_mul_f32 v[194:195], v[194:195], v[32:33]
	global_store_dwordx4 v37, v[164:167], s[20:21]
	global_store_dwordx4 v37, v[168:171], s[20:21] offset:16
	global_store_dwordx4 v37, v[172:175], s[20:21] offset:2048
	global_store_dwordx4 v37, v[176:179], s[20:21] offset:2064
	s_add_u32 s20, s20, 0x1000
	s_addc_u32 s21, s21, 0
	global_store_dwordx4 v37, v[180:183], s[20:21]
	global_store_dwordx4 v37, v[184:187], s[20:21] offset:16
	global_store_dwordx4 v37, v[188:191], s[20:21] offset:2048
	global_store_dwordx4 v37, v[192:195], s[20:21] offset:2064
	s_add_u32 s20, s20, 0x1000
	s_addc_u32 s21, s21, 0
	s_waitcnt vmcnt(36)
	v_lshlrev_b32_e32 v44, 16, v132
	v_and_b32_e32 v45, 0xffff0000, v132
	v_lshlrev_b32_e32 v46, 16, v133
	v_and_b32_e32 v47, 0xffff0000, v133
	v_lshlrev_b32_e32 v48, 16, v134
	v_and_b32_e32 v49, 0xffff0000, v134
	v_lshlrev_b32_e32 v50, 16, v135
	v_and_b32_e32 v51, 0xffff0000, v135
	v_lshlrev_b32_e32 v52, 16, v136
	v_and_b32_e32 v53, 0xffff0000, v136
	v_lshlrev_b32_e32 v54, 16, v137
	v_and_b32_e32 v55, 0xffff0000, v137
	v_lshlrev_b32_e32 v56, 16, v138
	v_and_b32_e32 v57, 0xffff0000, v138
	v_lshlrev_b32_e32 v58, 16, v139
	v_and_b32_e32 v59, 0xffff0000, v139
	v_lshlrev_b32_e32 v60, 16, v140
	v_and_b32_e32 v61, 0xffff0000, v140
	v_lshlrev_b32_e32 v62, 16, v141
	v_and_b32_e32 v63, 0xffff0000, v141
	v_lshlrev_b32_e32 v64, 16, v142
	v_and_b32_e32 v65, 0xffff0000, v142
	v_lshlrev_b32_e32 v66, 16, v143
	v_and_b32_e32 v67, 0xffff0000, v143
	v_lshlrev_b32_e32 v68, 16, v144
	v_and_b32_e32 v69, 0xffff0000, v144
	v_lshlrev_b32_e32 v70, 16, v145
	v_and_b32_e32 v71, 0xffff0000, v145
	v_lshlrev_b32_e32 v72, 16, v146
	v_and_b32_e32 v73, 0xffff0000, v146
	v_lshlrev_b32_e32 v74, 16, v147
	v_and_b32_e32 v75, 0xffff0000, v147
	v_pk_mul_f32 v[38:39], v[44:45], v[44:45]
	v_pk_fma_f32 v[38:39], v[46:47], v[46:47], v[38:39]
	v_pk_fma_f32 v[38:39], v[48:49], v[48:49], v[38:39]
	v_pk_fma_f32 v[38:39], v[50:51], v[50:51], v[38:39]
	v_pk_fma_f32 v[38:39], v[52:53], v[52:53], v[38:39]
	v_pk_fma_f32 v[38:39], v[54:55], v[54:55], v[38:39]
	v_pk_fma_f32 v[38:39], v[56:57], v[56:57], v[38:39]
	v_pk_fma_f32 v[38:39], v[58:59], v[58:59], v[38:39]
	v_pk_fma_f32 v[38:39], v[60:61], v[60:61], v[38:39]
	v_pk_fma_f32 v[38:39], v[62:63], v[62:63], v[38:39]
	v_pk_fma_f32 v[38:39], v[64:65], v[64:65], v[38:39]
	v_pk_fma_f32 v[38:39], v[66:67], v[66:67], v[38:39]
	v_pk_fma_f32 v[38:39], v[68:69], v[68:69], v[38:39]
	v_pk_fma_f32 v[38:39], v[70:71], v[70:71], v[38:39]
	v_pk_fma_f32 v[38:39], v[72:73], v[72:73], v[38:39]
	v_pk_fma_f32 v[38:39], v[74:75], v[74:75], v[38:39]
	v_add_f32_e32 v38, v38, v39
	s_nop 1
	v_add_f32_dpp v38, v38, v38 quad_perm:[1,0,3,2] row_mask:0xf bank_mask:0xf
	s_nop 1
	v_add_f32_dpp v38, v38, v38 quad_perm:[2,3,0,1] row_mask:0xf bank_mask:0xf
	s_nop 1
	v_add_f32_dpp v38, v38, v38 row_half_mirror row_mask:0xf bank_mask:0xf
	s_nop 1
	v_add_f32_dpp v38, v38, v38 row_mirror row_mask:0xf bank_mask:0xf
	s_nop 1
	v_add_f32_dpp v38, v38, v38 row_bcast:15 row_mask:0xa bank_mask:0xf
	s_nop 1
	v_add_f32_dpp v38, v38, v38 row_bcast:31 row_mask:0xc bank_mask:0xf
	s_nop 1
	v_readlane_b32 s100, v38, 63
	s_nop 3
	v_mov_b32_e32 v40, s100
	v_fma_f32 v40, v40, v43, v34
	v_rsq_f32_e32 v41, v40
	s_nop 0
	v_mul_f32_e32 v42, v40, v41
	v_mul_f32_e32 v42, v42, v41
	v_fmaak_f32 v42, -0.5, v42, 0x3fc00000
	v_mul_f32_e32 v40, v41, v42
	v_mov_b32_e32 v41, v40
	v_pk_mul_f32 v[44:45], v[44:45], v[40:41]
	v_pk_mul_f32 v[44:45], v[44:45], v[2:3]
	v_pk_mul_f32 v[46:47], v[46:47], v[40:41]
	v_pk_mul_f32 v[46:47], v[46:47], v[4:5]
	v_pk_mul_f32 v[48:49], v[48:49], v[40:41]
	v_pk_mul_f32 v[48:49], v[48:49], v[6:7]
	v_pk_mul_f32 v[50:51], v[50:51], v[40:41]
	v_pk_mul_f32 v[50:51], v[50:51], v[8:9]
	v_pk_mul_f32 v[52:53], v[52:53], v[40:41]
	v_pk_mul_f32 v[52:53], v[52:53], v[10:11]
	v_pk_mul_f32 v[54:55], v[54:55], v[40:41]
	v_pk_mul_f32 v[54:55], v[54:55], v[12:13]
	v_pk_mul_f32 v[56:57], v[56:57], v[40:41]
	v_pk_mul_f32 v[56:57], v[56:57], v[14:15]
	v_pk_mul_f32 v[58:59], v[58:59], v[40:41]
	v_pk_mul_f32 v[58:59], v[58:59], v[16:17]
	v_pk_mul_f32 v[60:61], v[60:61], v[40:41]
	v_pk_mul_f32 v[60:61], v[60:61], v[18:19]
	v_pk_mul_f32 v[62:63], v[62:63], v[40:41]
	v_pk_mul_f32 v[62:63], v[62:63], v[20:21]
	v_pk_mul_f32 v[64:65], v[64:65], v[40:41]
	v_pk_mul_f32 v[64:65], v[64:65], v[22:23]
	v_pk_mul_f32 v[66:67], v[66:67], v[40:41]
	v_pk_mul_f32 v[66:67], v[66:67], v[24:25]
	v_pk_mul_f32 v[68:69], v[68:69], v[40:41]
	v_pk_mul_f32 v[68:69], v[68:69], v[26:27]
	v_pk_mul_f32 v[70:71], v[70:71], v[40:41]
	v_pk_mul_f32 v[70:71], v[70:71], v[28:29]
	v_pk_mul_f32 v[72:73], v[72:73], v[40:41]
	v_pk_mul_f32 v[72:73], v[72:73], v[30:31]
	v_pk_mul_f32 v[74:75], v[74:75], v[40:41]
	v_pk_mul_f32 v[74:75], v[74:75], v[32:33]
	global_store_dwordx4 v37, v[44:47], s[20:21]
	global_store_dwordx4 v37, v[48:51], s[20:21] offset:16
	global_store_dwordx4 v37, v[52:55], s[20:21] offset:2048
	global_store_dwordx4 v37, v[56:59], s[20:21] offset:2064
	s_add_u32 s20, s20, 0x1000
	s_addc_u32 s21, s21, 0
	global_store_dwordx4 v37, v[60:63], s[20:21]
	global_store_dwordx4 v37, v[64:67], s[20:21] offset:16
	global_store_dwordx4 v37, v[68:71], s[20:21] offset:2048
	global_store_dwordx4 v37, v[72:75], s[20:21] offset:2064
	s_add_u32 s20, s20, 0x1000
	s_addc_u32 s21, s21, 0
	s_waitcnt vmcnt(32)
	v_lshlrev_b32_e32 v164, 16, v148
	v_and_b32_e32 v165, 0xffff0000, v148
	v_lshlrev_b32_e32 v166, 16, v149
	v_and_b32_e32 v167, 0xffff0000, v149
	v_lshlrev_b32_e32 v168, 16, v150
	v_and_b32_e32 v169, 0xffff0000, v150
	v_lshlrev_b32_e32 v170, 16, v151
	v_and_b32_e32 v171, 0xffff0000, v151
	v_lshlrev_b32_e32 v172, 16, v152
	v_and_b32_e32 v173, 0xffff0000, v152
	v_lshlrev_b32_e32 v174, 16, v153
	v_and_b32_e32 v175, 0xffff0000, v153
	v_lshlrev_b32_e32 v176, 16, v154
	v_and_b32_e32 v177, 0xffff0000, v154
	v_lshlrev_b32_e32 v178, 16, v155
	v_and_b32_e32 v179, 0xffff0000, v155
	v_lshlrev_b32_e32 v180, 16, v156
	v_and_b32_e32 v181, 0xffff0000, v156
	v_lshlrev_b32_e32 v182, 16, v157
	v_and_b32_e32 v183, 0xffff0000, v157
	v_lshlrev_b32_e32 v184, 16, v158
	v_and_b32_e32 v185, 0xffff0000, v158
	v_lshlrev_b32_e32 v186, 16, v159
	v_and_b32_e32 v187, 0xffff0000, v159
	v_lshlrev_b32_e32 v188, 16, v160
	v_and_b32_e32 v189, 0xffff0000, v160
	v_lshlrev_b32_e32 v190, 16, v161
	v_and_b32_e32 v191, 0xffff0000, v161
	v_lshlrev_b32_e32 v192, 16, v162
	v_and_b32_e32 v193, 0xffff0000, v162
	v_lshlrev_b32_e32 v194, 16, v163
	v_and_b32_e32 v195, 0xffff0000, v163
	v_pk_mul_f32 v[38:39], v[164:165], v[164:165]
	v_pk_fma_f32 v[38:39], v[166:167], v[166:167], v[38:39]
	v_pk_fma_f32 v[38:39], v[168:169], v[168:169], v[38:39]
	v_pk_fma_f32 v[38:39], v[170:171], v[170:171], v[38:39]
	v_pk_fma_f32 v[38:39], v[172:173], v[172:173], v[38:39]
	v_pk_fma_f32 v[38:39], v[174:175], v[174:175], v[38:39]
	v_pk_fma_f32 v[38:39], v[176:177], v[176:177], v[38:39]
	v_pk_fma_f32 v[38:39], v[178:179], v[178:179], v[38:39]
	v_pk_fma_f32 v[38:39], v[180:181], v[180:181], v[38:39]
	v_pk_fma_f32 v[38:39], v[182:183], v[182:183], v[38:39]
	v_pk_fma_f32 v[38:39], v[184:185], v[184:185], v[38:39]
	v_pk_fma_f32 v[38:39], v[186:187], v[186:187], v[38:39]
	v_pk_fma_f32 v[38:39], v[188:189], v[188:189], v[38:39]
	v_pk_fma_f32 v[38:39], v[190:191], v[190:191], v[38:39]
	v_pk_fma_f32 v[38:39], v[192:193], v[192:193], v[38:39]
	v_pk_fma_f32 v[38:39], v[194:195], v[194:195], v[38:39]
	v_add_f32_e32 v38, v38, v39
	s_nop 1
	v_add_f32_dpp v38, v38, v38 quad_perm:[1,0,3,2] row_mask:0xf bank_mask:0xf
	s_nop 1
	v_add_f32_dpp v38, v38, v38 quad_perm:[2,3,0,1] row_mask:0xf bank_mask:0xf
	s_nop 1
	v_add_f32_dpp v38, v38, v38 row_half_mirror row_mask:0xf bank_mask:0xf
	s_nop 1
	v_add_f32_dpp v38, v38, v38 row_mirror row_mask:0xf bank_mask:0xf
	s_nop 1
	v_add_f32_dpp v38, v38, v38 row_bcast:15 row_mask:0xa bank_mask:0xf
	s_nop 1
	v_add_f32_dpp v38, v38, v38 row_bcast:31 row_mask:0xc bank_mask:0xf
	s_nop 1
	v_readlane_b32 s100, v38, 63
	s_nop 3
	v_mov_b32_e32 v40, s100
	v_fma_f32 v40, v40, v43, v34
	v_rsq_f32_e32 v41, v40
	s_nop 0
	v_mul_f32_e32 v42, v40, v41
	v_mul_f32_e32 v42, v42, v41
	v_fmaak_f32 v42, -0.5, v42, 0x3fc00000
	v_mul_f32_e32 v40, v41, v42
	v_mov_b32_e32 v41, v40
	v_pk_mul_f32 v[164:165], v[164:165], v[40:41]
	v_pk_mul_f32 v[164:165], v[164:165], v[2:3]
	v_pk_mul_f32 v[166:167], v[166:167], v[40:41]
	v_pk_mul_f32 v[166:167], v[166:167], v[4:5]
	v_pk_mul_f32 v[168:169], v[168:169], v[40:41]
	v_pk_mul_f32 v[168:169], v[168:169], v[6:7]
	v_pk_mul_f32 v[170:171], v[170:171], v[40:41]
	v_pk_mul_f32 v[170:171], v[170:171], v[8:9]
	v_pk_mul_f32 v[172:173], v[172:173], v[40:41]
	v_pk_mul_f32 v[172:173], v[172:173], v[10:11]
	v_pk_mul_f32 v[174:175], v[174:175], v[40:41]
	v_pk_mul_f32 v[174:175], v[174:175], v[12:13]
	v_pk_mul_f32 v[176:177], v[176:177], v[40:41]
	v_pk_mul_f32 v[176:177], v[176:177], v[14:15]
	v_pk_mul_f32 v[178:179], v[178:179], v[40:41]
	v_pk_mul_f32 v[178:179], v[178:179], v[16:17]
	v_pk_mul_f32 v[180:181], v[180:181], v[40:41]
	v_pk_mul_f32 v[180:181], v[180:181], v[18:19]
	v_pk_mul_f32 v[182:183], v[182:183], v[40:41]
	v_pk_mul_f32 v[182:183], v[182:183], v[20:21]
	v_pk_mul_f32 v[184:185], v[184:185], v[40:41]
	v_pk_mul_f32 v[184:185], v[184:185], v[22:23]
	v_pk_mul_f32 v[186:187], v[186:187], v[40:41]
	v_pk_mul_f32 v[186:187], v[186:187], v[24:25]
	v_pk_mul_f32 v[188:189], v[188:189], v[40:41]
	v_pk_mul_f32 v[188:189], v[188:189], v[26:27]
	v_pk_mul_f32 v[190:191], v[190:191], v[40:41]
	v_pk_mul_f32 v[190:191], v[190:191], v[28:29]
	v_pk_mul_f32 v[192:193], v[192:193], v[40:41]
	v_pk_mul_f32 v[192:193], v[192:193], v[30:31]
	v_pk_mul_f32 v[194:195], v[194:195], v[40:41]
	v_pk_mul_f32 v[194:195], v[194:195], v[32:33]
	global_store_dwordx4 v37, v[164:167], s[20:21]
	global_store_dwordx4 v37, v[168:171], s[20:21] offset:16
	global_store_dwordx4 v37, v[172:175], s[20:21] offset:2048
	global_store_dwordx4 v37, v[176:179], s[20:21] offset:2064
	s_add_u32 s20, s20, 0x1000
	s_addc_u32 s21, s21, 0
	global_store_dwordx4 v37, v[180:183], s[20:21]
	global_store_dwordx4 v37, v[184:187], s[20:21] offset:16
	global_store_dwordx4 v37, v[188:191], s[20:21] offset:2048
	global_store_dwordx4 v37, v[192:195], s[20:21] offset:2064
	s_add_u32 s20, s20, 0x1000
	s_addc_u32 s21, s21, 0
	s_endpgm
.Lfn_orig:
	v_and_b32_e32 v10, 63, v0
	v_and_b32_e32 v0, 64, v1
	v_add_u32_e32 v0, 64, v0
	v_xor_b32_e32 v2, 1, v1
	v_cmp_lt_i32_e32 vcc, v2, v0
	v_readlane_b32 s2, v253, 2
	v_readlane_b32 s3, v253, 3
	v_cndmask_b32_e32 v2, v1, v2, vcc
	v_lshlrev_b32_e32 v14, 2, v2
	v_xor_b32_e32 v2, 2, v1
	v_cmp_lt_i32_e32 vcc, v2, v0
	s_load_dword s1, s[2:3], 0x0
	s_load_dwordx4 s[4:7], s[96:97], 0xa8
	s_load_dwordx2 s[10:11], s[96:97], 0xb8
	v_cndmask_b32_e32 v2, v1, v2, vcc
	v_lshlrev_b32_e32 v15, 2, v2
	v_xor_b32_e32 v2, 4, v1
	v_cmp_lt_i32_e32 vcc, v2, v0
	s_waitcnt lgkmcnt(0)
	s_lshl_b32 s2, s1, 3
	s_ashr_i32 s1, s0, 31
	v_cndmask_b32_e32 v2, v1, v2, vcc
	v_lshlrev_b32_e32 v16, 2, v2
	v_xor_b32_e32 v2, 8, v1
	v_cmp_lt_i32_e32 vcc, v2, v0
	v_readlane_b32 s3, v254, 16
	v_lshlrev_b32_e32 v12, 5, v10
	v_cndmask_b32_e32 v2, v1, v2, vcc
	v_lshlrev_b32_e32 v17, 2, v2
	v_xor_b32_e32 v2, 16, v1
	v_cmp_lt_i32_e32 vcc, v2, v0
	v_mov_b32_e32 v13, 0
	s_add_u32 s0, s0, s3
	v_cndmask_b32_e32 v2, v1, v2, vcc
	v_lshlrev_b32_e32 v18, 2, v2
	v_xor_b32_e32 v2, 32, v1
	v_cmp_lt_i32_e32 vcc, v2, v0
	v_readlane_b32 s3, v254, 58
	v_mov_b32_e32 v3, v13
	v_cndmask_b32_e32 v0, v1, v2, vcc
	v_or_b32_e32 v2, 0x1000, v12
	v_or_b32_e32 v4, 0x1010, v12
	v_mov_b32_e32 v5, v13
	v_or_b32_e32 v6, 0x1800, v12
	v_mov_b32_e32 v7, v13
	v_or_b32_e32 v8, 0x1810, v12
	v_mov_b32_e32 v9, v13
	s_addc_u32 s1, s1, s3
	v_lshlrev_b32_e32 v19, 2, v0
	v_lshl_add_u64 v[0:1], s[4:5], 0, v[12:13]
	v_lshl_add_u64 v[2:3], s[4:5], 0, v[2:3]
	v_lshl_add_u64 v[4:5], s[4:5], 0, v[4:5]
	v_lshl_add_u64 v[6:7], s[4:5], 0, v[6:7]
	v_lshl_add_u64 v[8:9], s[4:5], 0, v[8:9]
	s_lshl_b64 s[4:5], s[0:1], 12
	s_add_u32 s4, s10, s4
	v_lshlrev_b32_e32 v10, 4, v10
	v_mov_b32_e32 v11, v13
	s_addc_u32 s5, s11, s5
	v_lshl_add_u64 v[10:11], s[4:5], 0, v[10:11]
	s_mov_b64 s[4:5], 0x19624800
	s_ashr_i32 s3, s2, 31
	v_lshl_add_u64 v[10:11], v[10:11], 0, s[4:5]
	s_lshl_b64 s[4:5], s[2:3], 12
	s_lshl_b64 s[0:1], s[0:1], 13
	s_add_u32 s0, s6, s0
	s_addc_u32 s1, s7, s1
	v_lshl_add_u64 v[12:13], s[0:1], 0, v[12:13]
	s_mov_b64 s[0:1], 0x1000
	v_lshl_add_u64 v[12:13], v[12:13], 0, s[0:1]
	s_lshl_b64 s[6:7], s[2:3], 13
	v_mov_b32_e32 v20, 0x358637bd
	s_mov_b32 s3, 0xf800000
	v_mov_b32_e32 v21, 0x260
